# P2 queue: MoBA units ordered (b,h)-major (all 16 query blocks of a (b,h) adjacent) for K/V block reuse in L2/MALL
# baseline (speedup 1.0000x reference)
; __global__ void __launch_bounds__(512) hybrid_fwd(Params p) {
;     ...
;             if (C.tid == 0) s_unit = (int)atomicAdd(ctl + 64 * (1 + l), 1u);
;             __syncthreads();
;             const int u = s_unit;
;             __syncthreads();
;             if (u >= 1024 + 1024 + 512) break;
;             const int v2 = u - 512, grpq = v2 >> 7, rq = v2 & 127;
;     ...
;             if (u >= 512 && rq < 64) lru_unit(C, p, l, grpq * 64 + rq);
;     ...
;             if (u >= 512 && rq >= 64) moba_unit(C, grpq * 64 + (rq - 64), (const float*)(C.ws + WS_KM) + (size_t)l * 128 * 512);
.LBB0_321:
	s_or_b64 exec, exec, s[40:41]
	s_waitcnt lgkmcnt(0)
	s_barrier
	ds_read_b32 v0, v193
	s_movk_i32 s19, 0x9ff
	s_mov_b64 s[40:41], -1
	s_waitcnt lgkmcnt(0)
	s_barrier
	v_cmp_lt_i32_e32 vcc, s19, v0
	v_readfirstlane_b32 s74, v0
	s_cbranch_vccnz .LBB0_316
	s_cmp_lt_u32 s74, 512
	s_cbranch_scc1 .Lq3_done
	s_sub_u32 s19, s74, 512
	s_bitcmp1_b32 s19, 6
	s_cbranch_scc0 .Lq3_done
	s_lshr_b32 s20, s19, 7
	s_lshl_b32 s20, s20, 2
	s_bfe_u32 s21, s19, 0x20004
	s_add_u32 s20, s20, s21
	s_and_b32 s21, s19, 15
	s_lshl_b32 s21, s21, 7
	s_add_u32 s20, s20, s21
	s_add_u32 s74, s20, 576
